# proj (seg2/3, seg5/6) and outproj epilogues: next-tile register prefetch issued after the epilogue's own loads so they do not queue behind it on vmcnt
# baseline (speedup 1.0000x reference)
.LBB0_107:
	v_readlane_b32 s4, v254, 45
	s_add_i32 s10, s11, s4
	v_readlane_b32 s5, v254, 46
	s_cmpk_gt_i32 s10, 0x3ff
	s_cselect_b64 s[4:5], -1, 0
	s_and_b64 vcc, exec, s[4:5]
	s_branch .LBB0_109

.Lop_base:
	s_nop 3
	s_lshl_b32 s14, s13, 12
	s_add_u32 s14, s14, s56
	s_add_u32 s6, s6, s14
	s_addc_u32 s7, s7, 0
	v_lshl_add_u32 v110, v150, 12, v0
	global_load_dwordx4 v[6:9], v110, s[6:7]
	s_add_u32 s6, s6, 0x8000
	s_addc_u32 s7, s7, 0
	global_load_dwordx4 v[10:13], v110, s[6:7]
	s_add_u32 s6, s6, 0x8000
	s_addc_u32 s7, s7, 0
	global_load_dwordx4 v[14:17], v110, s[6:7]
	s_add_u32 s6, s6, 0x8000
	s_addc_u32 s7, s7, 0
	global_load_dwordx4 v[18:21], v110, s[6:7]
	s_add_u32 s6, s6, 0x8000
	s_addc_u32 s7, s7, 0
	global_load_dwordx4 v[22:25], v110, s[6:7]
	s_add_u32 s6, s6, 0x8000
	s_addc_u32 s7, s7, 0
	global_load_dwordx4 v[26:29], v110, s[6:7]
	s_add_u32 s6, s6, 0x8000
	s_addc_u32 s7, s7, 0
	global_load_dwordx4 v[30:33], v110, s[6:7]
	s_add_u32 s6, s6, 0x8000
	s_addc_u32 s7, s7, 0
	global_load_dwordx4 v[34:37], v110, s[6:7]
	s_add_u32 s6, s6, 0x8000
	s_addc_u32 s7, s7, 0
	global_load_dwordx4 v[38:41], v110, s[6:7]
	s_add_u32 s6, s6, 0x8000
	s_addc_u32 s7, s7, 0
	global_load_dwordx4 v[42:45], v110, s[6:7]
	s_add_u32 s6, s6, 0x8000
	s_addc_u32 s7, s7, 0
	global_load_dwordx4 v[46:49], v110, s[6:7]
	s_add_u32 s6, s6, 0x8000
	s_addc_u32 s7, s7, 0
	global_load_dwordx4 v[50:53], v110, s[6:7]
	s_add_u32 s6, s6, 0x8000
	s_addc_u32 s7, s7, 0
	global_load_dwordx4 v[54:57], v110, s[6:7]
	s_add_u32 s6, s6, 0x8000
	s_addc_u32 s7, s7, 0
	global_load_dwordx4 v[58:61], v110, s[6:7]
	s_add_u32 s6, s6, 0x8000
	s_addc_u32 s7, s7, 0
	global_load_dwordx4 v[62:65], v110, s[6:7]
	s_add_u32 s6, s6, 0x8000
	s_addc_u32 s7, s7, 0
	global_load_dwordx4 v[98:101], v110, s[6:7]
	s_and_b64 vcc, exec, s[4:5]
	s_cbranch_vccnz .Lop_dummy
	s_lshl_b32 s6, s10, 4
	s_and_b32 s6, s6, 0xffffff80
	s_lshl_b32 s7, s10, 7
	v_add_u32_e32 v66, s6, v146
	s_and_b32 s7, s7, 0x380
	v_ashrrev_i32_e32 v67, 31, v66
	v_lshlrev_b64 v[66:67], 11, v[66:67]
	v_add_u32_e32 v68, s7, v146
	v_lshl_add_u64 v[66:67], v[130:131], 0, v[66:67]
	v_ashrrev_i32_e32 v69, 31, v68
	v_lshlrev_b64 v[68:69], 11, v[68:69]
	v_add_co_u32_e32 v70, vcc, 0x10000, v66
	v_lshl_add_u64 v[68:69], v[132:133], 0, v[68:69]
	s_nop 0
	v_addc_co_u32_e32 v71, vcc, 0, v67, vcc
	v_add_co_u32_e32 v72, vcc, 0x10000, v68
	global_load_dwordx4 v[86:89], v[66:67], off
	global_load_dwordx4 v[82:85], v[68:69], off
	v_addc_co_u32_e32 v73, vcc, 0, v69, vcc
	global_load_dwordx4 v[94:97], v[70:71], off
	global_load_dwordx4 v[74:77], v[72:73], off
	v_add_co_u32_e32 v70, vcc, 0x20000, v66
	s_nop 1
	v_addc_co_u32_e32 v71, vcc, 0, v67, vcc
	v_add_co_u32_e32 v72, vcc, 0x20000, v68
	s_nop 1
	v_addc_co_u32_e32 v73, vcc, 0, v69, vcc
	v_add_co_u32_e32 v66, vcc, 0x30000, v66
	global_load_dwordx4 v[90:93], v[70:71], off
	s_nop 0
	global_load_dwordx4 v[70:73], v[72:73], off
	v_addc_co_u32_e32 v67, vcc, 0, v67, vcc
	v_add_co_u32_e32 v68, vcc, 0x30000, v68
	s_nop 1
	v_addc_co_u32_e32 v69, vcc, 0, v69, vcc
	global_load_dwordx4 v[78:81], v[66:67], off
	s_nop 0
	global_load_dwordx4 v[66:69], v[68:69], off
	s_branch .Lop_pfdone
.Lop_dummy:
	global_load_dwordx4 v[86:89], v110, s[6:7]
	global_load_dwordx4 v[82:85], v110, s[6:7]
	global_load_dwordx4 v[94:97], v110, s[6:7]
	global_load_dwordx4 v[74:77], v110, s[6:7]
	global_load_dwordx4 v[90:93], v110, s[6:7]
	global_load_dwordx4 v[70:73], v110, s[6:7]
	global_load_dwordx4 v[78:81], v110, s[6:7]
	global_load_dwordx4 v[66:69], v110, s[6:7]
.Lop_pfdone:
	v_add_u32_e32 v114, s12, v150
	v_mov_b32_e32 v115, 0
	v_lshlrev_b64 v[114:115], 12, v[114:115]
	v_lshl_add_u64 v[112:113], v[136:137], 0, s[56:57]
	v_lshl_add_u64 v[112:113], v[112:113], 0, v[114:115]
	s_mov_b32 s98, 0x8000
	s_mov_b32 s99, 0
	ds_read_b128 v[102:105], v151
	ds_read_b128 v[106:109], v151 offset:4224
	s_waitcnt vmcnt(23) lgkmcnt(1)
	v_pk_fma_f32 v[6:7], v[2:3], v[102:103], v[6:7]
	v_pk_fma_f32 v[8:9], v[4:5], v[104:105], v[8:9]
	global_store_dwordx4 v[112:113], v[6:9], off
	v_lshl_add_u64 v[112:113], v[112:113], 0, s[98:99]
	ds_read_b128 v[102:105], v151 offset:8448
	s_waitcnt vmcnt(23) lgkmcnt(1)
	v_pk_fma_f32 v[10:11], v[2:3], v[106:107], v[10:11]
	v_pk_fma_f32 v[12:13], v[4:5], v[108:109], v[12:13]
	global_store_dwordx4 v[112:113], v[10:13], off
	v_lshl_add_u64 v[112:113], v[112:113], 0, s[98:99]
	ds_read_b128 v[106:109], v151 offset:12672
	s_waitcnt vmcnt(23) lgkmcnt(1)
	v_pk_fma_f32 v[14:15], v[2:3], v[102:103], v[14:15]
	v_pk_fma_f32 v[16:17], v[4:5], v[104:105], v[16:17]
	global_store_dwordx4 v[112:113], v[14:17], off
	v_lshl_add_u64 v[112:113], v[112:113], 0, s[98:99]
	ds_read_b128 v[102:105], v151 offset:16896
	s_waitcnt vmcnt(23) lgkmcnt(1)
	v_pk_fma_f32 v[18:19], v[2:3], v[106:107], v[18:19]
	v_pk_fma_f32 v[20:21], v[4:5], v[108:109], v[20:21]
	global_store_dwordx4 v[112:113], v[18:21], off
	v_lshl_add_u64 v[112:113], v[112:113], 0, s[98:99]
	ds_read_b128 v[106:109], v151 offset:21120
	s_waitcnt vmcnt(23) lgkmcnt(1)
	v_pk_fma_f32 v[22:23], v[2:3], v[102:103], v[22:23]
	v_pk_fma_f32 v[24:25], v[4:5], v[104:105], v[24:25]
	global_store_dwordx4 v[112:113], v[22:25], off
	v_lshl_add_u64 v[112:113], v[112:113], 0, s[98:99]
	ds_read_b128 v[102:105], v151 offset:25344
	s_waitcnt vmcnt(23) lgkmcnt(1)
	v_pk_fma_f32 v[26:27], v[2:3], v[106:107], v[26:27]
	v_pk_fma_f32 v[28:29], v[4:5], v[108:109], v[28:29]
	global_store_dwordx4 v[112:113], v[26:29], off
	v_lshl_add_u64 v[112:113], v[112:113], 0, s[98:99]
	ds_read_b128 v[106:109], v151 offset:29568
	s_waitcnt vmcnt(23) lgkmcnt(1)
	v_pk_fma_f32 v[30:31], v[2:3], v[102:103], v[30:31]
	v_pk_fma_f32 v[32:33], v[4:5], v[104:105], v[32:33]
	global_store_dwordx4 v[112:113], v[30:33], off
	v_lshl_add_u64 v[112:113], v[112:113], 0, s[98:99]
	ds_read_b128 v[102:105], v151 offset:33792
	s_waitcnt vmcnt(23) lgkmcnt(1)
	v_pk_fma_f32 v[34:35], v[2:3], v[106:107], v[34:35]
	v_pk_fma_f32 v[36:37], v[4:5], v[108:109], v[36:37]
	global_store_dwordx4 v[112:113], v[34:37], off
	v_lshl_add_u64 v[112:113], v[112:113], 0, s[98:99]
	ds_read_b128 v[106:109], v151 offset:38016
	s_waitcnt vmcnt(23) lgkmcnt(1)
	v_pk_fma_f32 v[38:39], v[2:3], v[102:103], v[38:39]
	v_pk_fma_f32 v[40:41], v[4:5], v[104:105], v[40:41]
	global_store_dwordx4 v[112:113], v[38:41], off
	v_lshl_add_u64 v[112:113], v[112:113], 0, s[98:99]
	ds_read_b128 v[102:105], v151 offset:42240
	s_waitcnt vmcnt(23) lgkmcnt(1)
	v_pk_fma_f32 v[42:43], v[2:3], v[106:107], v[42:43]
	v_pk_fma_f32 v[44:45], v[4:5], v[108:109], v[44:45]
	global_store_dwordx4 v[112:113], v[42:45], off
	v_lshl_add_u64 v[112:113], v[112:113], 0, s[98:99]
	ds_read_b128 v[106:109], v151 offset:46464
	s_waitcnt vmcnt(23) lgkmcnt(1)
	v_pk_fma_f32 v[46:47], v[2:3], v[102:103], v[46:47]
	v_pk_fma_f32 v[48:49], v[4:5], v[104:105], v[48:49]
	global_store_dwordx4 v[112:113], v[46:49], off
	v_lshl_add_u64 v[112:113], v[112:113], 0, s[98:99]
	ds_read_b128 v[102:105], v151 offset:50688
	s_waitcnt vmcnt(23) lgkmcnt(1)
	v_pk_fma_f32 v[50:51], v[2:3], v[106:107], v[50:51]
	v_pk_fma_f32 v[52:53], v[4:5], v[108:109], v[52:53]
	global_store_dwordx4 v[112:113], v[50:53], off
	v_lshl_add_u64 v[112:113], v[112:113], 0, s[98:99]
	ds_read_b128 v[106:109], v151 offset:54912
	s_waitcnt vmcnt(23) lgkmcnt(1)
	v_pk_fma_f32 v[54:55], v[2:3], v[102:103], v[54:55]
	v_pk_fma_f32 v[56:57], v[4:5], v[104:105], v[56:57]
	global_store_dwordx4 v[112:113], v[54:57], off
	v_lshl_add_u64 v[112:113], v[112:113], 0, s[98:99]
	ds_read_b128 v[102:105], v151 offset:59136
	s_waitcnt vmcnt(23) lgkmcnt(1)
	v_pk_fma_f32 v[58:59], v[2:3], v[106:107], v[58:59]
	v_pk_fma_f32 v[60:61], v[4:5], v[108:109], v[60:61]
	global_store_dwordx4 v[112:113], v[58:61], off
	v_lshl_add_u64 v[112:113], v[112:113], 0, s[98:99]
	ds_read_b128 v[106:109], v151 offset:63360
	s_waitcnt vmcnt(23) lgkmcnt(1)
	v_pk_fma_f32 v[62:63], v[2:3], v[102:103], v[62:63]
	v_pk_fma_f32 v[64:65], v[4:5], v[104:105], v[64:65]
	global_store_dwordx4 v[112:113], v[62:65], off
	v_lshl_add_u64 v[112:113], v[112:113], 0, s[98:99]
	s_waitcnt vmcnt(23) lgkmcnt(0)
	v_pk_fma_f32 v[98:99], v[2:3], v[106:107], v[98:99]
	v_pk_fma_f32 v[100:101], v[4:5], v[108:109], v[100:101]
	global_store_dwordx4 v[112:113], v[98:101], off
	s_branch .LBB0_100

.LBB0_451:
	v_readlane_b32 s6, v254, 45
	s_add_i32 s34, s34, s6
	v_readlane_b32 s7, v254, 46
	s_cmpk_gt_i32 s34, 0x9ff
	s_cselect_b64 s[6:7], -1, 0
	s_and_b64 vcc, exec, s[6:7]
	s_cbranch_vccnz .LBB0_453
	s_lshr_b32 s8, s12, 2
	s_cmp_eq_u32 s8, 1
	s_cbranch_scc1 .LBB0_453
	s_sub_u32 s8, s12, 10
	s_cmp_lt_u32 s8, 4
	s_cbranch_scc1 .LBB0_453
	s_mul_hi_i32 s8, s34, 0x66666667
	s_lshr_b32 s9, s8, 31
	s_ashr_i32 s8, s8, 3
	s_add_i32 s8, s8, s9
	v_lshl_add_u32 v66, s8, 7, v148
	s_mul_i32 s9, s8, 20
	v_ashrrev_i32_e32 v67, 31, v66
	s_sub_i32 s9, s34, s9
	v_lshlrev_b64 v[66:67], 11, v[66:67]
	v_lshl_add_u64 v[90:91], v[130:131], 0, v[66:67]
	v_lshl_add_u32 v66, s9, 7, v148
	v_ashrrev_i32_e32 v67, 31, v66
	v_lshlrev_b64 v[66:67], 11, v[66:67]
	v_add_co_u32_e32 v74, vcc, 0x10000, v90
	v_lshl_add_u64 v[92:93], v[132:133], 0, v[66:67]
	s_nop 0
	v_addc_co_u32_e32 v75, vcc, 0, v91, vcc
	v_add_co_u32_e32 v78, vcc, 0x10000, v92
	global_load_dwordx4 v[70:73], v[90:91], off
	global_load_dwordx4 v[66:69], v[92:93], off
	v_addc_co_u32_e32 v79, vcc, 0, v93, vcc
	v_add_co_u32_e32 v82, vcc, 0x20000, v90
	global_load_dwordx4 v[74:77], v[74:75], off
	s_nop 0
	global_load_dwordx4 v[78:81], v[78:79], off
	v_addc_co_u32_e32 v83, vcc, 0, v91, vcc
	v_add_co_u32_e32 v86, vcc, 0x20000, v92
	s_nop 1
	v_addc_co_u32_e32 v87, vcc, 0, v93, vcc
	v_add_co_u32_e32 v90, vcc, 0x30000, v90
	global_load_dwordx4 v[82:85], v[82:83], off
	s_nop 0
	global_load_dwordx4 v[86:89], v[86:87], off
	v_addc_co_u32_e32 v91, vcc, 0, v91, vcc
	v_add_co_u32_e32 v94, vcc, 0x30000, v92
	s_nop 1
	v_addc_co_u32_e32 v95, vcc, 0, v93, vcc
	global_load_dwordx4 v[90:93], v[90:91], off
	s_nop 0
	global_load_dwordx4 v[94:97], v[94:95], off

.LBB0_470:
	s_andn2_b64 vcc, exec, s[12:13]
	s_cbranch_vccnz .LBB0_488
	s_cmp_eq_u32 s19, 5
	s_cselect_b64 s[14:15], -1, 0
	v_readlane_b32 s72, v250, 18
	s_and_b64 s[10:11], s[14:15], exec
	v_readlane_b32 s76, v250, 22
	v_readlane_b32 s78, v250, 24
	v_readlane_b32 s77, v250, 23
	v_readlane_b32 s79, v250, 25
	s_cselect_b32 s11, s76, s78
	v_ashrrev_i32_e32 v27, 31, v26
	s_cselect_b32 s10, s77, s79
	s_add_u32 s12, s11, s2
	v_lshl_add_u64 v[2:3], v[26:27], 4, s[0:1]
	s_addc_u32 s13, s10, s3
	v_or_b32_e32 v2, v2, v25
	v_readlane_b32 s10, v251, 55
	v_lshlrev_b64 v[2:3], 16, v[2:3]
	v_readlane_b32 s11, v251, 56
	v_lshlrev_b32_e32 v4, 8, v0
	v_mov_b32_e32 v5, v1
	v_lshl_add_u64 v[2:3], s[10:11], 0, v[2:3]
	v_lshl_add_u64 v[34:35], v[2:3], 0, v[4:5]
	ds_read2_b32 v[14:15], v155 offset0:6 offset1:7
	ds_read2_b32 v[16:17], v155 offset0:14 offset1:15
	ds_read2_b32 v[22:23], v155 offset0:22 offset1:23
	ds_read2_b32 v[50:51], v155 offset0:16 offset1:17
	ds_read2_b32 v[48:49], v155 offset0:18 offset1:19
	s_waitcnt vmcnt(5)
	ds_read2_b32 v[108:109], v155 offset1:1
	ds_read2_b32 v[18:19], v155 offset0:8 offset1:9
	ds_read2_b32 v[38:39], v155 offset0:24 offset1:25
	ds_read2_b32 v[40:41], v155 offset0:26 offset1:27
	ds_read2_b32 v[42:43], v155 offset0:28 offset1:29
	ds_read2_b32 v[46:47], v155 offset0:20 offset1:21
	ds_read2_b32 v[44:45], v155 offset0:30 offset1:31
	global_load_dwordx4 v[2:5], v1, s[12:13] offset:16
	global_load_dwordx4 v[6:9], v1, s[12:13] offset:48
	global_load_dwordx4 v[10:13], v1, s[12:13] offset:32
	global_load_dwordx4 v[104:107], v1, s[12:13]
	global_load_dwordx4 v[124:127], v1, s[12:13]
	global_load_dwordx4 v[142:145], v1, s[12:13] offset:16
	global_load_dwordx4 v[158:161], v1, s[12:13] offset:32
	global_load_dwordx4 v[162:165], v1, s[12:13] offset:48
	global_load_dwordx4 v[166:169], v1, s[12:13] offset:64
	global_load_dwordx4 v[170:173], v1, s[12:13] offset:80
	global_load_dwordx4 v[174:177], v1, s[12:13] offset:96
	global_load_dwordx4 v[178:181], v1, s[12:13] offset:112
	v_lshrrev_b32_e32 v248, 6, v0
	v_lshlrev_b32_e32 v248, 6, v248
	s_and_saveexec_b64 s[16:17], s[42:43]
	global_load_dwordx4 v[182:185], v248, s[62:63]
	global_load_dwordx4 v[186:189], v248, s[62:63] offset:16
	global_load_dwordx4 v[190:193], v248, s[62:63] offset:32
	global_load_dwordx4 v[194:197], v248, s[62:63] offset:48
	global_load_dwordx4 v[208:211], v[136:137], off
	global_load_dwordx4 v[214:217], v[136:137], off offset:16
	global_load_dwordx4 v[228:231], v[136:137], off offset:32
	global_load_dwordx4 v[244:247], v[136:137], off offset:48
	s_or_b64 exec, exec, s[16:17]
	s_and_b64 vcc, exec, s[6:7]
	s_cbranch_vccnz .Lpje_b_nopf
	s_mul_hi_i32 s8, s34, 0x66666667
	s_lshr_b32 s9, s8, 31
	s_ashr_i32 s8, s8, 3
	s_add_i32 s8, s8, s9
	v_lshl_add_u32 v66, s8, 7, v148
	s_mul_i32 s9, s8, 20
	v_ashrrev_i32_e32 v67, 31, v66
	s_sub_i32 s9, s34, s9
	v_lshlrev_b64 v[66:67], 11, v[66:67]
	v_lshl_add_u64 v[90:91], v[130:131], 0, v[66:67]
	v_lshl_add_u32 v66, s9, 7, v148
	v_ashrrev_i32_e32 v67, 31, v66
	v_lshlrev_b64 v[66:67], 11, v[66:67]
	v_add_co_u32_e32 v74, vcc, 0x10000, v90
	v_lshl_add_u64 v[92:93], v[132:133], 0, v[66:67]
	s_nop 0
	v_addc_co_u32_e32 v75, vcc, 0, v91, vcc
	v_add_co_u32_e32 v78, vcc, 0x10000, v92
	global_load_dwordx4 v[70:73], v[90:91], off
	global_load_dwordx4 v[66:69], v[92:93], off
	v_addc_co_u32_e32 v79, vcc, 0, v93, vcc
	v_add_co_u32_e32 v82, vcc, 0x20000, v90
	global_load_dwordx4 v[74:77], v[74:75], off
	s_nop 0
	global_load_dwordx4 v[78:81], v[78:79], off
	v_addc_co_u32_e32 v83, vcc, 0, v91, vcc
	v_add_co_u32_e32 v86, vcc, 0x20000, v92
	s_nop 1
	v_addc_co_u32_e32 v87, vcc, 0, v93, vcc
	v_add_co_u32_e32 v90, vcc, 0x30000, v90
	global_load_dwordx4 v[82:85], v[82:83], off
	s_nop 0
	global_load_dwordx4 v[86:89], v[86:87], off
	v_addc_co_u32_e32 v91, vcc, 0, v91, vcc
	v_add_co_u32_e32 v94, vcc, 0x30000, v92
	s_nop 1
	v_addc_co_u32_e32 v95, vcc, 0, v93, vcc
	global_load_dwordx4 v[90:93], v[90:91], off
	s_nop 0
	global_load_dwordx4 v[94:97], v[94:95], off
.Lpje_b_nopf:
	s_waitcnt lgkmcnt(6)
	v_pk_mul_f32 v[98:99], v[108:109], v[108:109]
	s_waitcnt lgkmcnt(5)
	v_pk_mul_f32 v[64:65], v[18:19], v[18:19]
	v_mov_b32_e32 v100, v108
	v_mov_b32_e32 v101, v19
	v_mov_b32_e32 v19, v109
	ds_read2_b32 v[108:109], v155 offset0:2 offset1:3
	s_waitcnt vmcnt(22)
	ds_read2_b32 v[118:119], v155 offset0:12 offset1:13
	v_add_f32_e32 v27, v98, v99
	v_pk_mul_f32 v[58:59], v[50:51], v[50:51]
	v_pk_mul_f32 v[60:61], v[48:49], v[48:49]
	s_waitcnt lgkmcnt(3)
	v_pk_mul_f32 v[62:63], v[46:47], v[46:47]
	v_pk_mul_f32 v[54:55], v[22:23], v[22:23]
	v_pk_mul_f32 v[56:57], v[38:39], v[38:39]
	v_pk_mul_f32 v[20:21], v[40:41], v[40:41]
	v_pk_mul_f32 v[36:37], v[42:43], v[42:43]
	s_waitcnt lgkmcnt(2)
	v_pk_mul_f32 v[52:53], v[44:45], v[44:45]
	s_cmp_eq_u32 s19, 6
	s_cselect_b64 s[10:11], -1, 0
	s_and_b64 s[10:11], s[10:11], s[40:41]
	v_readlane_b32 s73, v250, 19
	v_readlane_b32 s74, v250, 20
	v_readlane_b32 s75, v250, 21
	v_readlane_b32 s80, v250, 26
	v_readlane_b32 s81, v250, 27
	v_readlane_b32 s82, v250, 28
	v_readlane_b32 s83, v250, 29
	v_readlane_b32 s84, v250, 30
	v_readlane_b32 s85, v250, 31
	v_readlane_b32 s86, v250, 32
	v_readlane_b32 s87, v250, 33
	s_waitcnt lgkmcnt(0)
	v_pk_mul_f32 v[120:121], v[118:119], v[118:119]
	s_waitcnt vmcnt(17)
	v_mov_b32_e32 v103, v11
	s_and_b64 vcc, exec, s[6:7]
	s_cbranch_vccnz .Lpje_b_w0
	s_waitcnt vmcnt(8)
	s_branch .Lpje_b_wd

.Lpje_b_wd:
	v_mov_b32_e32 v102, v104
	v_mov_b32_e32 v11, v105
	ds_read2_b32 v[104:105], v155 offset0:10 offset1:11
	v_mov_b32_e32 v116, v106
	v_mov_b32_e32 v117, v13
	v_mov_b32_e32 v13, v107
	ds_read2_b32 v[106:107], v155 offset0:4 offset1:5
	v_pk_mul_f32 v[110:111], v[108:109], v[108:109]
	s_waitcnt lgkmcnt(1)
	v_pk_mul_f32 v[112:113], v[104:105], v[104:105]
	v_add_f32_e32 v27, v27, v110
	v_mov_b32_e32 v114, v108
	v_mov_b32_e32 v115, v105
	v_mov_b32_e32 v105, v109
	s_waitcnt lgkmcnt(0)
	v_pk_mul_f32 v[108:109], v[106:107], v[106:107]
	v_add_f32_e32 v27, v27, v111
	v_add_f32_e32 v27, v27, v108
	v_add_f32_e32 v27, v27, v109
	v_fmac_f32_e32 v27, v14, v14
	v_fmac_f32_e32 v27, v15, v15
	v_add_f32_e32 v27, v27, v64
	v_add_f32_e32 v27, v27, v65
	v_add_f32_e32 v27, v27, v112
	v_add_f32_e32 v27, v27, v113
	v_add_f32_e32 v27, v27, v120
	v_add_f32_e32 v27, v27, v121
	v_fmac_f32_e32 v27, v16, v16
	v_fmac_f32_e32 v27, v17, v17
	v_add_f32_e32 v27, v27, v58
	v_add_f32_e32 v27, v27, v59
	v_add_f32_e32 v27, v27, v60
	v_add_f32_e32 v27, v27, v61
	v_add_f32_e32 v27, v27, v62
	v_add_f32_e32 v27, v27, v63
	v_add_f32_e32 v27, v27, v54
	v_add_f32_e32 v27, v27, v55
	v_add_f32_e32 v27, v27, v56
	v_add_f32_e32 v27, v27, v57
	v_add_f32_e32 v20, v27, v20
	v_add_f32_e32 v20, v20, v21
	v_add_f32_e32 v20, v20, v36
	v_add_f32_e32 v20, v20, v37
	v_add_f32_e32 v20, v20, v52
	v_add_f32_e32 v20, v20, v53
	v_fmamk_f32 v20, v20, 0x3d000000, v213
	v_cmp_gt_f32_e32 vcc, s54, v20
	v_mul_f32_e32 v21, 0x4b800000, v20
	s_nop 0
	v_cndmask_b32_e32 v20, v20, v21, vcc
	v_rsq_f32_e32 v20, v20
	s_nop 0
	v_mul_f32_e32 v21, 0x45800000, v20
	v_cndmask_b32_e32 v52, v20, v21, vcc
	v_pk_mul_f32 v[18:19], v[18:19], v[52:53] op_sel_hi:[1,0]
	v_pk_mul_f32 v[20:21], v[100:101], v[52:53] op_sel_hi:[1,0]
	v_pk_mul_f32 v[54:55], v[10:11], v[18:19]
	v_pk_mul_f32 v[10:11], v[114:115], v[52:53] op_sel_hi:[1,0]
	v_pk_mul_f32 v[60:61], v[102:103], v[20:21]
	v_pk_mul_f32 v[62:63], v[116:117], v[10:11]
	v_pk_mul_f32 v[10:11], v[104:105], v[52:53] op_sel_hi:[1,0]
	s_nop 0
	v_pk_mul_f32 v[56:57], v[12:13], v[10:11]
	v_mov_b32_e32 v10, v106
	v_mov_b32_e32 v11, v119
	v_pk_mul_f32 v[10:11], v[10:11], v[52:53] op_sel_hi:[1,0]
	v_mov_b32_e32 v12, v2
	v_mov_b32_e32 v13, v7
	v_mov_b32_e32 v119, v107
	v_mul_f32_e32 v2, v14, v52
	v_pk_mul_f32 v[64:65], v[12:13], v[10:11]
	v_pk_mul_f32 v[10:11], v[118:119], v[52:53] op_sel_hi:[1,0]
	v_mov_b32_e32 v7, v3
	v_mul_f32_e32 v20, v2, v4
	v_mul_f32_e32 v2, v16, v52
	v_mov_b32_e32 v14, v17
	v_pk_mul_f32 v[58:59], v[10:11], v[6:7]
	v_mul_f32_e32 v7, v2, v8
	v_pk_mul_f32 v[2:3], v[14:15], v[52:53] op_sel_hi:[1,0]
	v_mov_b32_e32 v4, v9
	v_pk_mul_f32 v[98:99], v[2:3], v[4:5]
	s_and_saveexec_b64 s[16:17], s[10:11]
	s_cbranch_execz .LBB0_473
	v_mov_b32_e32 v2, v60
	v_mov_b32_e32 v3, v55
	v_mov_b32_e32 v4, v62
	v_mov_b32_e32 v5, v57
	global_store_dwordx4 v[34:35], v[2:5], off
	v_mov_b32_e32 v18, v64
	v_mov_b32_e32 v19, v59
	v_mov_b32_e32 v2, v99
	v_mov_b32_e32 v3, v54
	v_mov_b32_e32 v4, v61
	v_mov_b32_e32 v5, v56
	global_store_dwordx4 v[34:35], v[2:5], off offset:28
	v_mov_b32_e32 v6, v65
	global_store_dwordx3 v[34:35], v[18:20], off offset:16
	v_mov_b32_e32 v4, v63
	v_mov_b32_e32 v5, v58
	global_store_dwordx4 v[34:35], v[4:7], off offset:44
	global_store_dword v[34:35], v98, off offset:60

.LBB0_507:
	s_and_b64 vcc, exec, s[10:11]
	s_cbranch_vccz .LBB0_525
	s_cmp_eq_u32 s19, 3
	v_readlane_b32 s72, v252, 2
	s_cselect_b64 s[10:11], -1, 0
	s_cmp_eq_u32 s19, 2
	v_readlane_b32 s86, v252, 16
	v_readlane_b32 s16, v250, 18
	v_readlane_b32 s87, v252, 17
	v_readlane_b32 s17, v250, 19
	s_cselect_b32 s12, s86, s16
	s_mov_b32 s14, 0xc885100
	s_cselect_b32 s13, s87, s17
	s_cselect_b32 s14, s14, 0xd085100
	s_add_u32 s12, s12, s4
	s_addc_u32 s13, s13, s5
	ds_read2_b32 v[34:35], v155 offset1:1
	ds_read2_b32 v[36:37], v155 offset0:2 offset1:3
	ds_read2_b32 v[38:39], v155 offset0:4 offset1:5
	ds_read2_b32 v[40:41], v155 offset0:6 offset1:7
	ds_read2_b32 v[42:43], v155 offset0:8 offset1:9
	ds_read2_b32 v[44:45], v155 offset0:10 offset1:11
	ds_read2_b32 v[46:47], v155 offset0:12 offset1:13
	ds_read2_b32 v[48:49], v155 offset0:14 offset1:15
	ds_read2_b32 v[50:51], v155 offset0:16 offset1:17
	ds_read2_b32 v[52:53], v155 offset0:18 offset1:19
	ds_read2_b32 v[54:55], v155 offset0:20 offset1:21
	ds_read2_b32 v[56:57], v155 offset0:22 offset1:23
	ds_read2_b32 v[58:59], v155 offset0:24 offset1:25
	ds_read2_b32 v[60:61], v155 offset0:26 offset1:27
	ds_read2_b32 v[62:63], v155 offset0:28 offset1:29
	ds_read2_b32 v[64:65], v155 offset0:30 offset1:31
	ds_read2_b32 v[98:99], v155 offset0:32 offset1:33
	ds_read2_b32 v[100:101], v155 offset0:34 offset1:35
	ds_read2_b32 v[102:103], v155 offset0:36 offset1:37
	ds_read2_b32 v[104:105], v155 offset0:38 offset1:39
	ds_read2_b32 v[106:107], v155 offset0:40 offset1:41
	ds_read2_b32 v[108:109], v155 offset0:42 offset1:43
	ds_read2_b32 v[110:111], v155 offset0:44 offset1:45
	ds_read2_b32 v[112:113], v155 offset0:46 offset1:47
	ds_read2_b32 v[114:115], v155 offset0:48 offset1:49
	ds_read2_b32 v[116:117], v155 offset0:50 offset1:51
	ds_read2_b32 v[118:119], v155 offset0:52 offset1:53
	ds_read2_b32 v[120:121], v155 offset0:54 offset1:55
	ds_read2_b32 v[122:123], v155 offset0:56 offset1:57
	ds_read2_b32 v[124:125], v155 offset0:58 offset1:59
	ds_read2_b32 v[126:127], v155 offset0:60 offset1:61
	ds_read2_b32 v[128:129], v155 offset0:62 offset1:63
	global_load_dwordx4 v[158:161], v1, s[12:13]
	global_load_dwordx4 v[162:165], v1, s[12:13] offset:16
	global_load_dwordx4 v[166:169], v1, s[12:13] offset:32
	global_load_dwordx4 v[170:173], v1, s[12:13] offset:48
	global_load_dwordx4 v[174:177], v1, s[12:13] offset:64
	global_load_dwordx4 v[178:181], v1, s[12:13] offset:80
	global_load_dwordx4 v[182:185], v1, s[12:13] offset:96
	global_load_dwordx4 v[186:189], v1, s[12:13] offset:112
	global_load_dwordx4 v[190:193], v1, s[12:13] offset:128
	global_load_dwordx4 v[194:197], v1, s[12:13] offset:144
	global_load_dwordx4 v[2:5], v1, s[12:13] offset:160
	global_load_dwordx4 v[6:9], v1, s[12:13] offset:176
	global_load_dwordx4 v[10:13], v1, s[12:13] offset:192
	global_load_dwordx4 v[14:17], v1, s[12:13] offset:208
	global_load_dwordx4 v[18:21], v1, s[12:13] offset:224
	global_load_dwordx4 v[28:31], v1, s[12:13] offset:240
	s_and_b64 vcc, exec, s[6:7]
	s_cbranch_vccnz .Lpje_d_nopf
	s_mul_hi_i32 s8, s34, 0x66666667
	s_lshr_b32 s9, s8, 31
	s_ashr_i32 s8, s8, 3
	s_add_i32 s8, s8, s9
	v_lshl_add_u32 v66, s8, 7, v148
	s_mul_i32 s9, s8, 20
	v_ashrrev_i32_e32 v67, 31, v66
	s_sub_i32 s9, s34, s9
	v_lshlrev_b64 v[66:67], 11, v[66:67]
	v_lshl_add_u64 v[90:91], v[130:131], 0, v[66:67]
	v_lshl_add_u32 v66, s9, 7, v148
	v_ashrrev_i32_e32 v67, 31, v66
	v_lshlrev_b64 v[66:67], 11, v[66:67]
	v_add_co_u32_e32 v74, vcc, 0x10000, v90
	v_lshl_add_u64 v[92:93], v[132:133], 0, v[66:67]
	s_nop 0
	v_addc_co_u32_e32 v75, vcc, 0, v91, vcc
	v_add_co_u32_e32 v78, vcc, 0x10000, v92
	global_load_dwordx4 v[70:73], v[90:91], off
	global_load_dwordx4 v[66:69], v[92:93], off
	v_addc_co_u32_e32 v79, vcc, 0, v93, vcc
	v_add_co_u32_e32 v82, vcc, 0x20000, v90
	global_load_dwordx4 v[74:77], v[74:75], off
	s_nop 0
	global_load_dwordx4 v[78:81], v[78:79], off
	v_addc_co_u32_e32 v83, vcc, 0, v91, vcc
	v_add_co_u32_e32 v86, vcc, 0x20000, v92
	s_nop 1
	v_addc_co_u32_e32 v87, vcc, 0, v93, vcc
	v_add_co_u32_e32 v90, vcc, 0x30000, v90
	global_load_dwordx4 v[82:85], v[82:83], off
	s_nop 0
	global_load_dwordx4 v[86:89], v[86:87], off
	v_addc_co_u32_e32 v91, vcc, 0, v91, vcc
	v_add_co_u32_e32 v94, vcc, 0x30000, v92
	s_nop 1
	v_addc_co_u32_e32 v95, vcc, 0, v93, vcc
	global_load_dwordx4 v[90:93], v[90:91], off
	s_nop 0
	global_load_dwordx4 v[94:97], v[94:95], off
.Lpje_d_nopf:
	s_add_u32 s14, s94, s14
	v_ashrrev_i32_e32 v27, 31, v26
	s_addc_u32 s15, s95, 0
	v_lshl_add_u64 v[26:27], v[26:27], 4, s[0:1]
	v_lshl_add_u64 v[32:33], v[32:33], 1, s[14:15]
	v_or_b32_e32 v26, v26, v25
	v_readlane_b32 s14, v251, 53
	v_lshlrev_b64 v[26:27], 16, v[26:27]
	v_readlane_b32 s15, v251, 54
	v_lshlrev_b32_e32 v0, 8, v0
	s_and_b64 s[10:11], s[10:11], s[40:41]
	v_lshl_add_u64 v[26:27], s[14:15], 0, v[26:27]
	v_lshl_add_u64 v[26:27], v[26:27], 0, v[0:1]
	v_readlane_b32 s73, v252, 3
	v_readlane_b32 s74, v252, 4
	v_readlane_b32 s75, v252, 5
	v_readlane_b32 s76, v252, 6
	v_readlane_b32 s77, v252, 7
	v_readlane_b32 s78, v252, 8
	v_readlane_b32 s79, v252, 9
	v_readlane_b32 s80, v252, 10
	v_readlane_b32 s81, v252, 11
	v_readlane_b32 s82, v252, 12
	v_readlane_b32 s83, v252, 13
	v_readlane_b32 s84, v252, 14
	v_readlane_b32 s85, v252, 15
	v_readlane_b32 s18, v250, 20
	v_readlane_b32 s19, v250, 21
	v_readlane_b32 s20, v250, 22
	v_readlane_b32 s21, v250, 23
	v_readlane_b32 s22, v250, 24
	v_readlane_b32 s23, v250, 25
	v_readlane_b32 s24, v250, 26
	v_readlane_b32 s25, v250, 27
	v_readlane_b32 s26, v250, 28
	v_readlane_b32 s27, v250, 29
	v_readlane_b32 s28, v250, 30
	v_readlane_b32 s29, v250, 31
	v_readlane_b32 s30, v250, 32
	v_readlane_b32 s31, v250, 33
	s_waitcnt lgkmcnt(15)
	v_pk_mul_f32 v[142:143], v[34:35], v[34:35]
	v_add_f32_e32 v0, v142, v143
	v_pk_mul_f32 v[144:145], v[36:37], v[36:37]
	v_add_f32_e32 v0, v0, v144
	v_add_f32_e32 v0, v0, v145
	v_pk_mul_f32 v[142:143], v[38:39], v[38:39]
	v_add_f32_e32 v0, v0, v142
	v_add_f32_e32 v0, v0, v143
	v_pk_mul_f32 v[144:145], v[40:41], v[40:41]
	v_add_f32_e32 v0, v0, v144
	v_add_f32_e32 v0, v0, v145
	v_pk_mul_f32 v[142:143], v[42:43], v[42:43]
	v_add_f32_e32 v0, v0, v142
	v_add_f32_e32 v0, v0, v143
	v_pk_mul_f32 v[144:145], v[44:45], v[44:45]
	v_add_f32_e32 v0, v0, v144
	v_add_f32_e32 v0, v0, v145
	v_pk_mul_f32 v[142:143], v[46:47], v[46:47]
	v_add_f32_e32 v0, v0, v142
	v_add_f32_e32 v0, v0, v143
	v_pk_mul_f32 v[144:145], v[48:49], v[48:49]
	v_add_f32_e32 v0, v0, v144
	v_add_f32_e32 v0, v0, v145
	v_pk_mul_f32 v[142:143], v[50:51], v[50:51]
	v_add_f32_e32 v0, v0, v142
	v_add_f32_e32 v0, v0, v143
	v_pk_mul_f32 v[144:145], v[52:53], v[52:53]
	v_add_f32_e32 v0, v0, v144
	v_add_f32_e32 v0, v0, v145
	v_pk_mul_f32 v[142:143], v[54:55], v[54:55]
	v_add_f32_e32 v0, v0, v142
	v_add_f32_e32 v0, v0, v143
	v_pk_mul_f32 v[144:145], v[56:57], v[56:57]
	v_add_f32_e32 v0, v0, v144
	v_add_f32_e32 v0, v0, v145
	v_pk_mul_f32 v[142:143], v[58:59], v[58:59]
	v_add_f32_e32 v0, v0, v142
	v_add_f32_e32 v0, v0, v143
	v_pk_mul_f32 v[144:145], v[60:61], v[60:61]
	v_add_f32_e32 v0, v0, v144
	v_add_f32_e32 v0, v0, v145
	v_pk_mul_f32 v[142:143], v[62:63], v[62:63]
	v_add_f32_e32 v0, v0, v142
	v_add_f32_e32 v0, v0, v143
	v_pk_mul_f32 v[144:145], v[64:65], v[64:65]
	v_add_f32_e32 v0, v0, v144
	v_add_f32_e32 v0, v0, v145
	v_pk_mul_f32 v[142:143], v[98:99], v[98:99]
	v_add_f32_e32 v0, v0, v142
	v_add_f32_e32 v0, v0, v143
	s_waitcnt lgkmcnt(14)
	v_pk_mul_f32 v[144:145], v[100:101], v[100:101]
	v_add_f32_e32 v0, v0, v144
	v_add_f32_e32 v0, v0, v145
	s_waitcnt lgkmcnt(13)
	v_pk_mul_f32 v[142:143], v[102:103], v[102:103]
	v_add_f32_e32 v0, v0, v142
	v_add_f32_e32 v0, v0, v143
	s_waitcnt lgkmcnt(12)
	v_pk_mul_f32 v[144:145], v[104:105], v[104:105]
	v_add_f32_e32 v0, v0, v144
	v_add_f32_e32 v0, v0, v145
	s_waitcnt lgkmcnt(11)
	v_pk_mul_f32 v[142:143], v[106:107], v[106:107]
	v_add_f32_e32 v0, v0, v142
	v_add_f32_e32 v0, v0, v143
	s_waitcnt lgkmcnt(10)
	v_pk_mul_f32 v[144:145], v[108:109], v[108:109]
	v_add_f32_e32 v0, v0, v144
	v_add_f32_e32 v0, v0, v145
	s_waitcnt lgkmcnt(9)
	v_pk_mul_f32 v[142:143], v[110:111], v[110:111]
	v_add_f32_e32 v0, v0, v142
	v_add_f32_e32 v0, v0, v143
	s_waitcnt lgkmcnt(8)
	v_pk_mul_f32 v[144:145], v[112:113], v[112:113]
	v_add_f32_e32 v0, v0, v144
	v_add_f32_e32 v0, v0, v145
	s_waitcnt lgkmcnt(7)
	v_pk_mul_f32 v[142:143], v[114:115], v[114:115]
	v_add_f32_e32 v0, v0, v142
	v_add_f32_e32 v0, v0, v143
	s_waitcnt lgkmcnt(6)
	v_pk_mul_f32 v[144:145], v[116:117], v[116:117]
	v_add_f32_e32 v0, v0, v144
	v_add_f32_e32 v0, v0, v145
	s_waitcnt lgkmcnt(5)
	v_pk_mul_f32 v[142:143], v[118:119], v[118:119]
	v_add_f32_e32 v0, v0, v142
	v_add_f32_e32 v0, v0, v143
	s_waitcnt lgkmcnt(4)
	v_pk_mul_f32 v[144:145], v[120:121], v[120:121]
	v_add_f32_e32 v0, v0, v144
	v_add_f32_e32 v0, v0, v145
	s_waitcnt lgkmcnt(3)
	v_pk_mul_f32 v[142:143], v[122:123], v[122:123]
	v_add_f32_e32 v0, v0, v142
	v_add_f32_e32 v0, v0, v143
	s_waitcnt lgkmcnt(2)
	v_pk_mul_f32 v[144:145], v[124:125], v[124:125]
	v_add_f32_e32 v0, v0, v144
	v_add_f32_e32 v0, v0, v145
	s_waitcnt lgkmcnt(1)
	v_pk_mul_f32 v[142:143], v[126:127], v[126:127]
	v_add_f32_e32 v0, v0, v142
	v_add_f32_e32 v0, v0, v143
	s_waitcnt lgkmcnt(0)
	v_pk_mul_f32 v[144:145], v[128:129], v[128:129]
	v_add_f32_e32 v0, v0, v144
	v_add_f32_e32 v0, v0, v145
	v_fmamk_f32 v0, v0, 0x3c800000, v213
	v_cmp_gt_f32_e32 vcc, s54, v0
	v_mul_f32_e32 v22, 0x4b800000, v0
	s_nop 0
	v_cndmask_b32_e32 v0, v0, v22, vcc
	v_rsq_f32_e32 v0, v0
	s_nop 0
	v_mul_f32_e32 v22, 0x45800000, v0
	v_cndmask_b32_e32 v146, v0, v22, vcc
	s_and_b64 vcc, exec, s[6:7]
	s_cbranch_vccnz .Lpje_d_w0
	s_waitcnt vmcnt(8)
	s_branch .Lpje_d_wd

.Lpje_d_wd:
	v_pk_mul_f32 v[34:35], v[34:35], v[146:147] op_sel_hi:[1,0]
	v_pk_mul_f32 v[36:37], v[36:37], v[146:147] op_sel_hi:[1,0]
	v_pk_mul_f32 v[38:39], v[38:39], v[146:147] op_sel_hi:[1,0]
	v_pk_mul_f32 v[40:41], v[40:41], v[146:147] op_sel_hi:[1,0]
	v_pk_mul_f32 v[34:35], v[34:35], v[158:159]
	v_pk_mul_f32 v[36:37], v[36:37], v[160:161]
	v_pk_mul_f32 v[38:39], v[38:39], v[162:163]
	v_pk_mul_f32 v[40:41], v[40:41], v[164:165]
	v_cvt_pk_bf16_f32 v158, v34, v35
	v_cvt_pk_bf16_f32 v159, v36, v37
	v_cvt_pk_bf16_f32 v160, v38, v39
	v_cvt_pk_bf16_f32 v161, v40, v41
	global_store_dwordx4 v[32:33], v[158:161], off
	v_pk_mul_f32 v[42:43], v[42:43], v[146:147] op_sel_hi:[1,0]
	v_pk_mul_f32 v[44:45], v[44:45], v[146:147] op_sel_hi:[1,0]
	v_pk_mul_f32 v[46:47], v[46:47], v[146:147] op_sel_hi:[1,0]
	v_pk_mul_f32 v[48:49], v[48:49], v[146:147] op_sel_hi:[1,0]
	v_pk_mul_f32 v[42:43], v[42:43], v[166:167]
	v_pk_mul_f32 v[44:45], v[44:45], v[168:169]
	v_pk_mul_f32 v[46:47], v[46:47], v[170:171]
	v_pk_mul_f32 v[48:49], v[48:49], v[172:173]
	v_cvt_pk_bf16_f32 v166, v42, v43
	v_cvt_pk_bf16_f32 v167, v44, v45
	v_cvt_pk_bf16_f32 v168, v46, v47
	v_cvt_pk_bf16_f32 v169, v48, v49
	global_store_dwordx4 v[32:33], v[166:169], off offset:16
	v_pk_mul_f32 v[50:51], v[50:51], v[146:147] op_sel_hi:[1,0]
	v_pk_mul_f32 v[52:53], v[52:53], v[146:147] op_sel_hi:[1,0]
	v_pk_mul_f32 v[54:55], v[54:55], v[146:147] op_sel_hi:[1,0]
	v_pk_mul_f32 v[56:57], v[56:57], v[146:147] op_sel_hi:[1,0]
	v_pk_mul_f32 v[50:51], v[50:51], v[174:175]
	v_pk_mul_f32 v[52:53], v[52:53], v[176:177]
	v_pk_mul_f32 v[54:55], v[54:55], v[178:179]
	v_pk_mul_f32 v[56:57], v[56:57], v[180:181]
	v_cvt_pk_bf16_f32 v174, v50, v51
	v_cvt_pk_bf16_f32 v175, v52, v53
	v_cvt_pk_bf16_f32 v176, v54, v55
	v_cvt_pk_bf16_f32 v177, v56, v57
	global_store_dwordx4 v[32:33], v[174:177], off offset:32
	v_pk_mul_f32 v[58:59], v[58:59], v[146:147] op_sel_hi:[1,0]
	v_pk_mul_f32 v[60:61], v[60:61], v[146:147] op_sel_hi:[1,0]
	v_pk_mul_f32 v[62:63], v[62:63], v[146:147] op_sel_hi:[1,0]
	v_pk_mul_f32 v[64:65], v[64:65], v[146:147] op_sel_hi:[1,0]
	v_pk_mul_f32 v[58:59], v[58:59], v[182:183]
	v_pk_mul_f32 v[60:61], v[60:61], v[184:185]
	v_pk_mul_f32 v[62:63], v[62:63], v[186:187]
	v_pk_mul_f32 v[64:65], v[64:65], v[188:189]
	v_cvt_pk_bf16_f32 v182, v58, v59
	v_cvt_pk_bf16_f32 v183, v60, v61
	v_cvt_pk_bf16_f32 v184, v62, v63
	v_cvt_pk_bf16_f32 v185, v64, v65
	global_store_dwordx4 v[32:33], v[182:185], off offset:48
	v_pk_mul_f32 v[98:99], v[98:99], v[146:147] op_sel_hi:[1,0]
	v_pk_mul_f32 v[100:101], v[100:101], v[146:147] op_sel_hi:[1,0]
	v_pk_mul_f32 v[102:103], v[102:103], v[146:147] op_sel_hi:[1,0]
	v_pk_mul_f32 v[104:105], v[104:105], v[146:147] op_sel_hi:[1,0]
	v_pk_mul_f32 v[98:99], v[98:99], v[190:191]
	v_pk_mul_f32 v[100:101], v[100:101], v[192:193]
	v_pk_mul_f32 v[102:103], v[102:103], v[194:195]
	v_pk_mul_f32 v[104:105], v[104:105], v[196:197]
	v_cvt_pk_bf16_f32 v190, v98, v99
	v_cvt_pk_bf16_f32 v191, v100, v101
	v_cvt_pk_bf16_f32 v192, v102, v103
	v_cvt_pk_bf16_f32 v193, v104, v105
	global_store_dwordx4 v[32:33], v[190:193], off offset:64
	v_pk_mul_f32 v[106:107], v[106:107], v[146:147] op_sel_hi:[1,0]
	v_pk_mul_f32 v[108:109], v[108:109], v[146:147] op_sel_hi:[1,0]
	v_pk_mul_f32 v[110:111], v[110:111], v[146:147] op_sel_hi:[1,0]
	v_pk_mul_f32 v[112:113], v[112:113], v[146:147] op_sel_hi:[1,0]
	v_pk_mul_f32 v[106:107], v[106:107], v[2:3]
	v_pk_mul_f32 v[108:109], v[108:109], v[4:5]
	v_pk_mul_f32 v[110:111], v[110:111], v[6:7]
	v_pk_mul_f32 v[112:113], v[112:113], v[8:9]
	v_cvt_pk_bf16_f32 v2, v106, v107
	v_cvt_pk_bf16_f32 v3, v108, v109
	v_cvt_pk_bf16_f32 v4, v110, v111
	v_cvt_pk_bf16_f32 v5, v112, v113
	global_store_dwordx4 v[32:33], v[2:5], off offset:80
	v_pk_mul_f32 v[114:115], v[114:115], v[146:147] op_sel_hi:[1,0]
	v_pk_mul_f32 v[116:117], v[116:117], v[146:147] op_sel_hi:[1,0]
	v_pk_mul_f32 v[118:119], v[118:119], v[146:147] op_sel_hi:[1,0]
	v_pk_mul_f32 v[120:121], v[120:121], v[146:147] op_sel_hi:[1,0]
	v_pk_mul_f32 v[114:115], v[114:115], v[10:11]
	v_pk_mul_f32 v[116:117], v[116:117], v[12:13]
	v_pk_mul_f32 v[118:119], v[118:119], v[14:15]
	v_pk_mul_f32 v[120:121], v[120:121], v[16:17]
	v_cvt_pk_bf16_f32 v10, v114, v115
	v_cvt_pk_bf16_f32 v11, v116, v117
	v_cvt_pk_bf16_f32 v12, v118, v119
	v_cvt_pk_bf16_f32 v13, v120, v121
	global_store_dwordx4 v[32:33], v[10:13], off offset:96
	v_pk_mul_f32 v[122:123], v[122:123], v[146:147] op_sel_hi:[1,0]
	v_pk_mul_f32 v[124:125], v[124:125], v[146:147] op_sel_hi:[1,0]
	v_pk_mul_f32 v[126:127], v[126:127], v[146:147] op_sel_hi:[1,0]
	v_pk_mul_f32 v[128:129], v[128:129], v[146:147] op_sel_hi:[1,0]
	v_pk_mul_f32 v[122:123], v[122:123], v[18:19]
	v_pk_mul_f32 v[124:125], v[124:125], v[20:21]
	v_pk_mul_f32 v[126:127], v[126:127], v[28:29]
	v_pk_mul_f32 v[128:129], v[128:129], v[30:31]
	v_cvt_pk_bf16_f32 v18, v122, v123
	v_cvt_pk_bf16_f32 v19, v124, v125
	v_cvt_pk_bf16_f32 v20, v126, v127
	v_cvt_pk_bf16_f32 v21, v128, v129
	global_store_dwordx4 v[32:33], v[18:21], off offset:112
	s_and_saveexec_b64 s[14:15], s[10:11]
	s_cbranch_execz .Lpje_d_skip
	global_store_dwordx4 v[26:27], v[34:37], off
	global_store_dwordx4 v[26:27], v[38:41], off offset:16
	global_store_dwordx4 v[26:27], v[42:45], off offset:32
	global_store_dwordx4 v[26:27], v[46:49], off offset:48
	global_store_dwordx4 v[26:27], v[50:53], off offset:64
	global_store_dwordx4 v[26:27], v[54:57], off offset:80
	global_store_dwordx4 v[26:27], v[58:61], off offset:96
	global_store_dwordx4 v[26:27], v[62:65], off offset:112
	global_store_dwordx4 v[26:27], v[98:101], off offset:128
	global_store_dwordx4 v[26:27], v[102:105], off offset:144
	global_store_dwordx4 v[26:27], v[106:109], off offset:160
	global_store_dwordx4 v[26:27], v[110:113], off offset:176
	global_store_dwordx4 v[26:27], v[114:117], off offset:192
	global_store_dwordx4 v[26:27], v[118:121], off offset:208
	global_store_dwordx4 v[26:27], v[122:125], off offset:224
	global_store_dwordx4 v[26:27], v[126:129], off offset:240
